# grid-barrier poll backoff removed: waiter poll loops use s_sleep 0 instead of s_sleep 1 between flag loads
# speedup vs baseline: 1.0073x; 1.0073x over previous
; __global__ void __launch_bounds__(512) mega(Params p, int ph_lo, int ph_hi) {
;     ...
;   if (ph_lo < 0) cg::this_grid().sync();
.LBB0_14:
	s_sleep 0
	global_load_dword v2, v0, s[4:5] offset:32 sc1
	s_waitcnt vmcnt(0)
	v_and_b32_e32 v2, 0xffff0000, v2
	v_cmp_ne_u32_e32 vcc, v2, v1
	s_or_b64 s[6:7], vcc, s[6:7]
	s_andn2_b64 exec, exec, s[6:7]
	s_cbranch_execnz .LBB0_14

; DI unsigned xb_ld(unsigned* p)              { return __hip_atomic_load(p, __ATOMIC_RELAXED, __HIP_MEMORY_SCOPE_AGENT); }
; DI void xcd_barrier_complete(unsigned* bar, unsigned x, unsigned& nloc, unsigned& nx) {
;   const unsigned G = gridDim.x * gridDim.y * gridDim.z;
;   unsigned sum, cnt, mine, sp = 0u;
;   for (;;) {
;     sum = 0u; cnt = 0u; mine = 0u;
; #pragma unroll
;     for (unsigned j = 0; j < 16; ++j) { const unsigned c = xb_ld(&bar[XB_XCNT(j)]); sum += c; cnt += (c > 0u) ? 1u : 0u; mine = (j == x) ? c : mine; }
;     if (sum == G) break;
;     __builtin_amdgcn_s_sleep(1);
;     if ((++sp & 255u) == 0u) { if (xb_ld(&bar[XB_TMO])) break; if (sp > XB_SPIN_CAP) { atomicAdd(&bar[XB_TMO], 1u); break; } }
;   }
;   nloc = mine > 0u ? mine : 1u; nx = cnt > 0u ? cnt : 1u;
; }
.LBB0_282:
	global_load_dword v15, v16, s[2:3] offset:1024 sc1
	global_load_dword v0, v16, s[2:3] offset:1280 sc1
	global_load_dword v1, v16, s[2:3] offset:1536 sc1
	global_load_dword v2, v16, s[2:3] offset:1792 sc1
	global_load_dword v3, v16, s[2:3] offset:2048 sc1
	global_load_dword v4, v16, s[2:3] offset:2304 sc1
	global_load_dword v5, v16, s[2:3] offset:2560 sc1
	global_load_dword v6, v16, s[2:3] offset:2816 sc1
	global_load_dword v7, v16, s[2:3] offset:3072 sc1
	global_load_dword v8, v16, s[2:3] offset:3328 sc1
	global_load_dword v9, v16, s[2:3] offset:3584 sc1
	global_load_dword v10, v16, s[2:3] offset:3840 sc1
	global_load_dword v11, v16, s[4:5] sc1
	global_load_dword v12, v16, s[6:7] sc1
	global_load_dword v13, v16, s[8:9] sc1
	global_load_dword v14, v16, s[10:11] sc1
	s_mov_b64 s[12:13], -1
	s_mov_b64 s[14:15], -1
	s_waitcnt vmcnt(14)
	v_add_u32_e32 v17, v0, v15
	s_waitcnt vmcnt(13)
	v_add_u32_e32 v17, v17, v1
	s_waitcnt vmcnt(12)
	v_add_u32_e32 v17, v17, v2
	s_waitcnt vmcnt(11)
	v_add_u32_e32 v17, v17, v3
	s_waitcnt vmcnt(10)
	v_add_u32_e32 v17, v17, v4
	s_waitcnt vmcnt(9)
	v_add_u32_e32 v17, v17, v5
	s_waitcnt vmcnt(8)
	v_add_u32_e32 v17, v17, v6
	s_waitcnt vmcnt(7)
	v_add_u32_e32 v17, v17, v7
	s_waitcnt vmcnt(6)
	v_add_u32_e32 v17, v17, v8
	s_waitcnt vmcnt(5)
	v_add_u32_e32 v17, v17, v9
	s_waitcnt vmcnt(4)
	v_add_u32_e32 v17, v17, v10
	s_waitcnt vmcnt(3)
	v_add_u32_e32 v17, v17, v11
	s_waitcnt vmcnt(2)
	v_add_u32_e32 v17, v17, v12
	s_waitcnt vmcnt(1)
	v_add_u32_e32 v17, v17, v13
	s_waitcnt vmcnt(0)
	v_add_u32_e32 v17, v17, v14
	v_cmp_eq_u32_e32 vcc, s18, v17
	s_cbranch_vccnz .LBB0_281
	s_and_b32 s12, s19, 0xff
	s_cmp_eq_u32 s12, 0
	s_mov_b64 s[12:13], -1
	s_mov_b64 s[16:17], -1
	s_sleep 0
	s_cbranch_scc0 .LBB0_286
	global_load_dword v17, v16, s[2:3] offset:512 sc1
	s_waitcnt vmcnt(0)
	v_cmp_eq_u32_e32 vcc, 0, v17
	s_cbranch_vccnz .LBB0_288
	s_mov_b64 s[16:17], 0

; DI unsigned xb_ld(unsigned* p)              { return __hip_atomic_load(p, __ATOMIC_RELAXED, __HIP_MEMORY_SCOPE_AGENT); }
; DI void xcd_barrier_complete(unsigned* bar, unsigned x, unsigned& nloc, unsigned& nx) {
;   const unsigned G = gridDim.x * gridDim.y * gridDim.z;
;   unsigned sum, cnt, mine, sp = 0u;
;   for (;;) {
;     sum = 0u; cnt = 0u; mine = 0u;
; #pragma unroll
;     for (unsigned j = 0; j < 16; ++j) { const unsigned c = xb_ld(&bar[XB_XCNT(j)]); sum += c; cnt += (c > 0u) ? 1u : 0u; mine = (j == x) ? c : mine; }
;     if (sum == G) break;
;     __builtin_amdgcn_s_sleep(1);
;     if ((++sp & 255u) == 0u) { if (xb_ld(&bar[XB_TMO])) break; if (sp > XB_SPIN_CAP) { atomicAdd(&bar[XB_TMO], 1u); break; } }
;   }
;   nloc = mine > 0u ? mine : 1u; nx = cnt > 0u ? cnt : 1u;
; }
.LBB0_507:
	global_load_dword v15, v145, s[4:5] offset:1024 sc1
	global_load_dword v0, v145, s[4:5] offset:1280 sc1
	global_load_dword v1, v145, s[4:5] offset:1536 sc1
	global_load_dword v2, v145, s[4:5] offset:1792 sc1
	global_load_dword v3, v145, s[4:5] offset:2048 sc1
	global_load_dword v4, v145, s[4:5] offset:2304 sc1
	global_load_dword v5, v145, s[4:5] offset:2560 sc1
	global_load_dword v6, v145, s[4:5] offset:2816 sc1
	global_load_dword v7, v145, s[4:5] offset:3072 sc1
	global_load_dword v8, v145, s[4:5] offset:3328 sc1
	global_load_dword v9, v145, s[4:5] offset:3584 sc1
	global_load_dword v10, v145, s[4:5] offset:3840 sc1
	global_load_dword v11, v145, s[10:11] sc1
	global_load_dword v12, v145, s[12:13] sc1
	global_load_dword v13, v145, s[14:15] sc1
	global_load_dword v14, v145, s[16:17] sc1
	s_mov_b64 s[18:19], -1
	s_mov_b64 s[20:21], -1
	s_waitcnt vmcnt(14)
	v_add_u32_e32 v16, v0, v15
	s_waitcnt vmcnt(13)
	v_add_u32_e32 v16, v16, v1
	s_waitcnt vmcnt(12)
	v_add_u32_e32 v16, v16, v2
	s_waitcnt vmcnt(11)
	v_add_u32_e32 v16, v16, v3
	s_waitcnt vmcnt(10)
	v_add_u32_e32 v16, v16, v4
	s_waitcnt vmcnt(9)
	v_add_u32_e32 v16, v16, v5
	s_waitcnt vmcnt(8)
	v_add_u32_e32 v16, v16, v6
	s_waitcnt vmcnt(7)
	v_add_u32_e32 v16, v16, v7
	s_waitcnt vmcnt(6)
	v_add_u32_e32 v16, v16, v8
	s_waitcnt vmcnt(5)
	v_add_u32_e32 v16, v16, v9
	s_waitcnt vmcnt(4)
	v_add_u32_e32 v16, v16, v10
	s_waitcnt vmcnt(3)
	v_add_u32_e32 v16, v16, v11
	s_waitcnt vmcnt(2)
	v_add_u32_e32 v16, v16, v12
	s_waitcnt vmcnt(1)
	v_add_u32_e32 v16, v16, v13
	s_waitcnt vmcnt(0)
	v_add_u32_e32 v16, v16, v14
	v_cmp_eq_u32_e32 vcc, s9, v16
	s_cbranch_vccnz .LBB0_506
	s_and_b32 s18, s24, 0xff
	s_cmp_eq_u32 s18, 0
	s_mov_b64 s[18:19], -1
	s_mov_b64 s[22:23], -1
	s_sleep 0
	s_cbranch_scc0 .LBB0_511
	global_load_dword v16, v145, s[4:5] offset:512 sc1
	s_waitcnt vmcnt(0)
	v_cmp_eq_u32_e32 vcc, 0, v16
	s_cbranch_vccnz .LBB0_513
	s_mov_b64 s[22:23], 0

; DI unsigned xb_ld(unsigned* p)              { return __hip_atomic_load(p, __ATOMIC_RELAXED, __HIP_MEMORY_SCOPE_AGENT); }
; DI void xcd_barrier_complete(unsigned* bar, unsigned x, unsigned& nloc, unsigned& nx) {
;   const unsigned G = gridDim.x * gridDim.y * gridDim.z;
;   unsigned sum, cnt, mine, sp = 0u;
;   for (;;) {
;     sum = 0u; cnt = 0u; mine = 0u;
; #pragma unroll
;     for (unsigned j = 0; j < 16; ++j) { const unsigned c = xb_ld(&bar[XB_XCNT(j)]); sum += c; cnt += (c > 0u) ? 1u : 0u; mine = (j == x) ? c : mine; }
;     if (sum == G) break;
;     __builtin_amdgcn_s_sleep(1);
;     if ((++sp & 255u) == 0u) { if (xb_ld(&bar[XB_TMO])) break; if (sp > XB_SPIN_CAP) { atomicAdd(&bar[XB_TMO], 1u); break; } }
;   }
;   nloc = mine > 0u ? mine : 1u; nx = cnt > 0u ? cnt : 1u;
; }
.LBB0_603:
	global_load_dword v15, v145, s[10:11] offset:1024 sc1
	global_load_dword v0, v145, s[10:11] offset:1280 sc1
	global_load_dword v1, v145, s[10:11] offset:1536 sc1
	global_load_dword v2, v145, s[10:11] offset:1792 sc1
	global_load_dword v3, v145, s[10:11] offset:2048 sc1
	global_load_dword v4, v145, s[10:11] offset:2304 sc1
	global_load_dword v5, v145, s[10:11] offset:2560 sc1
	global_load_dword v6, v145, s[10:11] offset:2816 sc1
	global_load_dword v7, v145, s[10:11] offset:3072 sc1
	global_load_dword v8, v145, s[10:11] offset:3328 sc1
	global_load_dword v9, v145, s[10:11] offset:3584 sc1
	global_load_dword v10, v145, s[10:11] offset:3840 sc1
	global_load_dword v11, v145, s[12:13] sc1
	global_load_dword v12, v145, s[14:15] sc1
	global_load_dword v13, v145, s[16:17] sc1
	global_load_dword v14, v145, s[18:19] sc1
	s_mov_b64 s[20:21], -1
	s_mov_b64 s[22:23], -1
	s_waitcnt vmcnt(14)
	v_add_u32_e32 v16, v0, v15
	s_waitcnt vmcnt(13)
	v_add_u32_e32 v16, v16, v1
	s_waitcnt vmcnt(12)
	v_add_u32_e32 v16, v16, v2
	s_waitcnt vmcnt(11)
	v_add_u32_e32 v16, v16, v3
	s_waitcnt vmcnt(10)
	v_add_u32_e32 v16, v16, v4
	s_waitcnt vmcnt(9)
	v_add_u32_e32 v16, v16, v5
	s_waitcnt vmcnt(8)
	v_add_u32_e32 v16, v16, v6
	s_waitcnt vmcnt(7)
	v_add_u32_e32 v16, v16, v7
	s_waitcnt vmcnt(6)
	v_add_u32_e32 v16, v16, v8
	s_waitcnt vmcnt(5)
	v_add_u32_e32 v16, v16, v9
	s_waitcnt vmcnt(4)
	v_add_u32_e32 v16, v16, v10
	s_waitcnt vmcnt(3)
	v_add_u32_e32 v16, v16, v11
	s_waitcnt vmcnt(2)
	v_add_u32_e32 v16, v16, v12
	s_waitcnt vmcnt(1)
	v_add_u32_e32 v16, v16, v13
	s_waitcnt vmcnt(0)
	v_add_u32_e32 v16, v16, v14
	v_cmp_eq_u32_e32 vcc, s9, v16
	s_cbranch_vccnz .LBB0_602
	s_and_b32 s20, s24, 0xff
	s_cmp_eq_u32 s20, 0
	s_mov_b64 s[20:21], -1
	s_mov_b64 s[28:29], -1
	s_sleep 0
	s_cbranch_scc0 .LBB0_607
	global_load_dword v16, v145, s[10:11] offset:512 sc1
	s_waitcnt vmcnt(0)
	v_cmp_eq_u32_e32 vcc, 0, v16
	s_cbranch_vccnz .LBB0_609
	s_mov_b64 s[28:29], 0

; DI unsigned xb_ld(unsigned* p)              { return __hip_atomic_load(p, __ATOMIC_RELAXED, __HIP_MEMORY_SCOPE_AGENT); }
; DI void xcd_barrier_complete(unsigned* bar, unsigned x, unsigned& nloc, unsigned& nx) {
;   const unsigned G = gridDim.x * gridDim.y * gridDim.z;
;   unsigned sum, cnt, mine, sp = 0u;
;   for (;;) {
;     sum = 0u; cnt = 0u; mine = 0u;
; #pragma unroll
;     for (unsigned j = 0; j < 16; ++j) { const unsigned c = xb_ld(&bar[XB_XCNT(j)]); sum += c; cnt += (c > 0u) ? 1u : 0u; mine = (j == x) ? c : mine; }
;     if (sum == G) break;
;     __builtin_amdgcn_s_sleep(1);
;     if ((++sp & 255u) == 0u) { if (xb_ld(&bar[XB_TMO])) break; if (sp > XB_SPIN_CAP) { atomicAdd(&bar[XB_TMO], 1u); break; } }
;   }
;   nloc = mine > 0u ? mine : 1u; nx = cnt > 0u ? cnt : 1u;
; }
.LBB0_1114:
	global_load_dword v15, v145, s[4:5] offset:1024 sc1
	global_load_dword v0, v145, s[4:5] offset:1280 sc1
	global_load_dword v1, v145, s[4:5] offset:1536 sc1
	global_load_dword v2, v145, s[4:5] offset:1792 sc1
	global_load_dword v3, v145, s[4:5] offset:2048 sc1
	global_load_dword v4, v145, s[4:5] offset:2304 sc1
	global_load_dword v5, v145, s[4:5] offset:2560 sc1
	global_load_dword v6, v145, s[4:5] offset:2816 sc1
	global_load_dword v7, v145, s[4:5] offset:3072 sc1
	global_load_dword v8, v145, s[4:5] offset:3328 sc1
	global_load_dword v9, v145, s[4:5] offset:3584 sc1
	global_load_dword v10, v145, s[4:5] offset:3840 sc1
	global_load_dword v11, v145, s[6:7] sc1
	global_load_dword v12, v145, s[10:11] sc1
	global_load_dword v13, v145, s[12:13] sc1
	global_load_dword v14, v145, s[14:15] sc1
	s_mov_b64 s[16:17], -1
	s_mov_b64 s[18:19], -1
	s_waitcnt vmcnt(14)
	v_add_u32_e32 v16, v0, v15
	s_waitcnt vmcnt(13)
	v_add_u32_e32 v16, v16, v1
	s_waitcnt vmcnt(12)
	v_add_u32_e32 v16, v16, v2
	s_waitcnt vmcnt(11)
	v_add_u32_e32 v16, v16, v3
	s_waitcnt vmcnt(10)
	v_add_u32_e32 v16, v16, v4
	s_waitcnt vmcnt(9)
	v_add_u32_e32 v16, v16, v5
	s_waitcnt vmcnt(8)
	v_add_u32_e32 v16, v16, v6
	s_waitcnt vmcnt(7)
	v_add_u32_e32 v16, v16, v7
	s_waitcnt vmcnt(6)
	v_add_u32_e32 v16, v16, v8
	s_waitcnt vmcnt(5)
	v_add_u32_e32 v16, v16, v9
	s_waitcnt vmcnt(4)
	v_add_u32_e32 v16, v16, v10
	s_waitcnt vmcnt(3)
	v_add_u32_e32 v16, v16, v11
	s_waitcnt vmcnt(2)
	v_add_u32_e32 v16, v16, v12
	s_waitcnt vmcnt(1)
	v_add_u32_e32 v16, v16, v13
	s_waitcnt vmcnt(0)
	v_add_u32_e32 v16, v16, v14
	v_cmp_eq_u32_e32 vcc, s22, v16
	s_cbranch_vccnz .LBB0_1113
	s_and_b32 s16, s23, 0xff
	s_cmp_eq_u32 s16, 0
	s_mov_b64 s[16:17], -1
	s_mov_b64 s[20:21], -1
	s_sleep 0
	s_cbranch_scc0 .LBB0_1118
	global_load_dword v16, v145, s[4:5] offset:512 sc1
	s_waitcnt vmcnt(0)
	v_cmp_eq_u32_e32 vcc, 0, v16
	s_cbranch_vccnz .LBB0_1120
	s_mov_b64 s[20:21], 0

; DI unsigned xb_ld(unsigned* p)              { return __hip_atomic_load(p, __ATOMIC_RELAXED, __HIP_MEMORY_SCOPE_AGENT); }
; DI void xcd_barrier_complete(unsigned* bar, unsigned x, unsigned& nloc, unsigned& nx) {
;   const unsigned G = gridDim.x * gridDim.y * gridDim.z;
;   unsigned sum, cnt, mine, sp = 0u;
;   for (;;) {
;     sum = 0u; cnt = 0u; mine = 0u;
; #pragma unroll
;     for (unsigned j = 0; j < 16; ++j) { const unsigned c = xb_ld(&bar[XB_XCNT(j)]); sum += c; cnt += (c > 0u) ? 1u : 0u; mine = (j == x) ? c : mine; }
;     if (sum == G) break;
;     __builtin_amdgcn_s_sleep(1);
;     if ((++sp & 255u) == 0u) { if (xb_ld(&bar[XB_TMO])) break; if (sp > XB_SPIN_CAP) { atomicAdd(&bar[XB_TMO], 1u); break; } }
;   }
;   nloc = mine > 0u ? mine : 1u; nx = cnt > 0u ? cnt : 1u;
; }
.LBB0_1580:
	global_load_dword v15, v145, s[4:5] offset:1024 sc1
	global_load_dword v0, v145, s[4:5] offset:1280 sc1
	global_load_dword v1, v145, s[4:5] offset:1536 sc1
	global_load_dword v2, v145, s[4:5] offset:1792 sc1
	global_load_dword v3, v145, s[4:5] offset:2048 sc1
	global_load_dword v4, v145, s[4:5] offset:2304 sc1
	global_load_dword v5, v145, s[4:5] offset:2560 sc1
	global_load_dword v6, v145, s[4:5] offset:2816 sc1
	global_load_dword v7, v145, s[4:5] offset:3072 sc1
	global_load_dword v8, v145, s[4:5] offset:3328 sc1
	global_load_dword v9, v145, s[4:5] offset:3584 sc1
	global_load_dword v10, v145, s[4:5] offset:3840 sc1
	global_load_dword v11, v145, s[6:7] sc1
	global_load_dword v12, v145, s[10:11] sc1
	global_load_dword v13, v145, s[12:13] sc1
	global_load_dword v14, v145, s[14:15] sc1
	s_mov_b64 s[16:17], -1
	s_mov_b64 s[18:19], -1
	s_waitcnt vmcnt(14)
	v_add_u32_e32 v16, v0, v15
	s_waitcnt vmcnt(13)
	v_add_u32_e32 v16, v16, v1
	s_waitcnt vmcnt(12)
	v_add_u32_e32 v16, v16, v2
	s_waitcnt vmcnt(11)
	v_add_u32_e32 v16, v16, v3
	s_waitcnt vmcnt(10)
	v_add_u32_e32 v16, v16, v4
	s_waitcnt vmcnt(9)
	v_add_u32_e32 v16, v16, v5
	s_waitcnt vmcnt(8)
	v_add_u32_e32 v16, v16, v6
	s_waitcnt vmcnt(7)
	v_add_u32_e32 v16, v16, v7
	s_waitcnt vmcnt(6)
	v_add_u32_e32 v16, v16, v8
	s_waitcnt vmcnt(5)
	v_add_u32_e32 v16, v16, v9
	s_waitcnt vmcnt(4)
	v_add_u32_e32 v16, v16, v10
	s_waitcnt vmcnt(3)
	v_add_u32_e32 v16, v16, v11
	s_waitcnt vmcnt(2)
	v_add_u32_e32 v16, v16, v12
	s_waitcnt vmcnt(1)
	v_add_u32_e32 v16, v16, v13
	s_waitcnt vmcnt(0)
	v_add_u32_e32 v16, v16, v14
	v_cmp_eq_u32_e32 vcc, s9, v16
	s_cbranch_vccnz .LBB0_1579
	s_and_b32 s16, s22, 0xff
	s_cmp_eq_u32 s16, 0
	s_mov_b64 s[16:17], -1
	s_mov_b64 s[20:21], -1
	s_sleep 0
	s_cbranch_scc0 .LBB0_1584
	global_load_dword v16, v145, s[4:5] offset:512 sc1
	s_waitcnt vmcnt(0)
	v_cmp_eq_u32_e32 vcc, 0, v16
	s_cbranch_vccnz .LBB0_1586
	s_mov_b64 s[20:21], 0
